# P4 channel-major epilogue also takes the context-row tiles (rinv=1, shift=0 through the same fma)
# speedup vs baseline: 1.0321x; 1.0040x over previous
; DEVI unsigned pk_bf16(float lo, float hi) { unsigned r; asm volatile("v_cvt_pk_bf16_f32 %0, %1, %2" : "=v"(r) : "v"(lo), "v"(hi)); return r; }
; template <class Epi>
; DEVI void gemm_phase(const Params& p, const u16* __restrict__ A, const u16* __restrict__ Bt, const int M, const int N, const int K, const int Msplit, const Epi& epi) {
;     ...
;         nrm = epi.ssq != nullptr && brow < TL;
;         if (nrm) {
;           if (tid2 < 256) { const float* q = epi.ssq + brow + tid2; rl[tid2] = rsqrtf(((q[0] + q[T]) + (q[2 * T] + q[3 * T])) * (1.f / D) + 1e-6f); }
;   DEVI void preload(Pre& q, int brow, int colb, int wr, int fr, int fq, bool nrm, int) const {
;     const int r = brow < TL ? (brow >> 12) : 8;
;     q.s0 = nrm ? sw[r * 2048 + colb + fr] : 0.f; q.s1 = nrm ? sw[r * 2048 + colb + 16 + fr] : 0.f;
;     q.invrev = exp2f(-(float)fr * (13.287712379549449f / 16.f)) * 0.15915494309189535f;
;   }
;   DEVI void operator()(int row0, int colb, int fr, const f32x4& b0, const f32x4& b1, const f32x4& rv, const bool nrm, const Pre& q) const {
;     f32x4 a0, a1;
; #pragma unroll
;     for (int j = 0; j < 4; ++j) { a0[j] = b0[j] * rv[j] + q.s0; a1[j] = b1[j] * rv[j] + q.s1; }
;     if (colb < 1280 || colb >= 1920) {
; #pragma unroll
;       for (int n = 0; n < 2; ++n) {
;         const int pc = colb + n * 16 + fr; const int ptc = pc < 1280 ? pc : pc - 640;
;         const f32x4& a = n ? a1 : a0;
;         uint2 o; o.x = pk_bf16(a[0], a[1]); o.y = pk_bf16(a[2], a[3]);
;         *(uint2*)(pt + (size_t)ptc * T + row0) = o;
;       }
.Lmy_p4_pt:
	v_mbcnt_lo_u32_b32 v208, -1, 0
	v_mbcnt_hi_u32_b32 v208, -1, v208
	s_lshr_b32 s52, s33, 6
	s_lshr_b32 s53, s52, 2
	s_and_b32 s54, s52, 3
	v_and_b32_e32 v209, 15, v208
	v_lshrrev_b32_e32 v210, 4, v208
	s_lshl_b32 s55, s52, 12
	s_add_u32 s55, s55, 0x20000
	s_cmp_eq_u32 s52, 7
	s_cselect_b32 s55, 0xd000, s55
	v_lshrrev_b32_e32 v211, 1, v210
	v_and_b32_e32 v212, 7, v209
	v_xor_b32_e32 v211, v211, v212
	v_and_b32_e32 v212, 1, v210
	v_lshlrev_b32_e32 v212, 3, v212
	v_lshl_add_u32 v212, v209, 7, v212
	v_add_u32_e32 v212, s55, v212
	v_lshl_add_u32 v184, v211, 4, v212
	v_xor_b32_e32 v148, 2, v211
	v_lshl_add_u32 v185, v148, 4, v212
	v_xor_b32_e32 v148, 4, v211
	v_lshl_add_u32 v186, v148, 4, v212
	v_xor_b32_e32 v148, 6, v211
	v_lshl_add_u32 v187, v148, 4, v212
	v_and_b32_e32 v149, 7, v208
	v_lshrrev_b32_e32 v150, 3, v208
	v_xor_b32_e32 v148, v149, v150
	v_lshlrev_b32_e32 v148, 4, v148
	v_lshl_add_u32 v188, v150, 7, v148
	v_add_u32_e32 v188, s55, v188
	s_lshl_b32 s58, s54, 5
	v_add_u32_e32 v148, s58, v150
	v_mul_u32_u24_e32 v148, 0x11000, v148
	s_lshl_b32 s58, s53, 7
	v_lshl_add_u32 v148, v149, 4, v148
	v_add_u32_e32 v189, s58, v148
	v_add_u32_e32 v190, 0x88000, v189
	s_lshl_b32 s58, s54, 7
	v_lshl_add_u32 v191, v209, 2, s58
	s_lshl_b32 s58, s53, 8
	v_lshl_add_u32 v192, v210, 4, s58
	s_lshr_b32 s58, s16, 4
	s_lshl_b32 s58, s58, 11
	s_add_u32 s58, s58, s40
	s_lshl_b32 s58, s58, 2
	s_add_u32 s44, s4, s58
	s_addc_u32 s45, s5, 0
	s_mul_i32 s58, s40, 0x11000
	s_lshl_b32 s59, s36, 1
	s_add_u32 s58, s58, s59
	s_add_u32 s46, s60, s58
	s_addc_u32 s47, s61, 0
	s_cmpk_lt_u32 s16, 0x80
	s_cbranch_scc1 .Lmy_p4_nrm
	v_mov_b32_e32 v128, 0
	v_mov_b32_e32 v129, 0
	v_mov_b32_e32 v130, 0
	v_mov_b32_e32 v131, 0
	v_mov_b32_e32 v152, 1.0
	v_mov_b32_e32 v153, 1.0
	v_mov_b32_e32 v154, 1.0
	v_mov_b32_e32 v155, 1.0
	v_mov_b32_e32 v156, 1.0
	v_mov_b32_e32 v157, 1.0
	v_mov_b32_e32 v158, 1.0
	v_mov_b32_e32 v159, 1.0
	v_mov_b32_e32 v160, 1.0
	v_mov_b32_e32 v161, 1.0
	v_mov_b32_e32 v162, 1.0
	v_mov_b32_e32 v163, 1.0
	v_mov_b32_e32 v164, 1.0
	v_mov_b32_e32 v165, 1.0
	v_mov_b32_e32 v166, 1.0
	v_mov_b32_e32 v167, 1.0
	v_mov_b32_e32 v168, 1.0
	v_mov_b32_e32 v169, 1.0
	v_mov_b32_e32 v170, 1.0
	v_mov_b32_e32 v171, 1.0
	v_mov_b32_e32 v172, 1.0
	v_mov_b32_e32 v173, 1.0
	v_mov_b32_e32 v174, 1.0
	v_mov_b32_e32 v175, 1.0
	v_mov_b32_e32 v176, 1.0
	v_mov_b32_e32 v177, 1.0
	v_mov_b32_e32 v178, 1.0
	v_mov_b32_e32 v179, 1.0
	v_mov_b32_e32 v180, 1.0
	v_mov_b32_e32 v181, 1.0
	v_mov_b32_e32 v182, 1.0
	v_mov_b32_e32 v183, 1.0
	s_branch .Lmy_p4_go
.Lmy_p4_nrm:
	global_load_dword v128, v191, s[44:45]
	global_load_dword v129, v191, s[44:45] offset:64
	global_load_dword v130, v191, s[44:45] offset:512
	global_load_dword v131, v191, s[44:45] offset:576
	ds_read_b128 v[152:155], v192 offset:49152
	ds_read_b128 v[156:159], v192 offset:49216
	ds_read_b128 v[160:163], v192 offset:49280
	ds_read_b128 v[164:167], v192 offset:49344
	ds_read_b128 v[168:171], v192 offset:49664
	ds_read_b128 v[172:175], v192 offset:49728
	ds_read_b128 v[176:179], v192 offset:49792
	ds_read_b128 v[180:183], v192 offset:49856
	s_waitcnt vmcnt(0) lgkmcnt(0)
.Lmy_p4_go:
	v_fma_f32 v120, v120, v152, v128
	v_fma_f32 v121, v121, v153, v128
	v_fma_f32 v122, v122, v154, v128
	v_fma_f32 v123, v123, v155, v128
	v_fma_f32 v112, v112, v156, v128
	v_fma_f32 v113, v113, v157, v128
	v_fma_f32 v114, v114, v158, v128
	v_fma_f32 v115, v115, v159, v128
	v_fma_f32 v104, v104, v160, v128
	v_fma_f32 v105, v105, v161, v128
	v_fma_f32 v106, v106, v162, v128
	v_fma_f32 v107, v107, v163, v128
	v_fma_f32 v96, v96, v164, v128
	v_fma_f32 v97, v97, v165, v128
	v_fma_f32 v98, v98, v166, v128
	v_fma_f32 v99, v99, v167, v128
	v_cvt_pk_bf16_f32 v120, v120, v121
	v_cvt_pk_bf16_f32 v121, v122, v123
	v_cvt_pk_bf16_f32 v112, v112, v113
	v_cvt_pk_bf16_f32 v113, v114, v115
	v_cvt_pk_bf16_f32 v104, v104, v105
	v_cvt_pk_bf16_f32 v105, v106, v107
	v_cvt_pk_bf16_f32 v96, v96, v97
	v_cvt_pk_bf16_f32 v97, v98, v99
	ds_write_b64 v184, v[120:121]
	ds_write_b64 v185, v[112:113]
	ds_write_b64 v186, v[104:105]
	ds_write_b64 v187, v[96:97]
	v_fma_f32 v124, v124, v152, v129
	v_fma_f32 v125, v125, v153, v129
	v_fma_f32 v126, v126, v154, v129
	v_fma_f32 v127, v127, v155, v129
	v_fma_f32 v116, v116, v156, v129
	v_fma_f32 v117, v117, v157, v129
	v_fma_f32 v118, v118, v158, v129
	v_fma_f32 v119, v119, v159, v129
	v_fma_f32 v108, v108, v160, v129
	v_fma_f32 v109, v109, v161, v129
	v_fma_f32 v110, v110, v162, v129
	v_fma_f32 v111, v111, v163, v129
	v_fma_f32 v100, v100, v164, v129
	v_fma_f32 v101, v101, v165, v129
	v_fma_f32 v102, v102, v166, v129
	v_fma_f32 v103, v103, v167, v129
	v_cvt_pk_bf16_f32 v124, v124, v125
	v_cvt_pk_bf16_f32 v125, v126, v127
	v_cvt_pk_bf16_f32 v116, v116, v117
	v_cvt_pk_bf16_f32 v117, v118, v119
	v_cvt_pk_bf16_f32 v108, v108, v109
	v_cvt_pk_bf16_f32 v109, v110, v111
	v_cvt_pk_bf16_f32 v100, v100, v101
	v_cvt_pk_bf16_f32 v101, v102, v103
	s_waitcnt lgkmcnt(0)
	ds_read_b128 v[132:135], v188
	ds_read_b128 v[136:139], v188 offset:1024
	ds_write_b64 v184, v[124:125] offset:2048
	ds_write_b64 v185, v[116:117] offset:2048
	ds_write_b64 v186, v[108:109] offset:2048
	ds_write_b64 v187, v[100:101] offset:2048
	v_fma_f32 v88, v88, v152, v130
	v_fma_f32 v89, v89, v153, v130
	v_fma_f32 v90, v90, v154, v130
	v_fma_f32 v91, v91, v155, v130
	v_fma_f32 v80, v80, v156, v130
	v_fma_f32 v81, v81, v157, v130
	v_fma_f32 v82, v82, v158, v130
	v_fma_f32 v83, v83, v159, v130
	v_fma_f32 v72, v72, v160, v130
	v_fma_f32 v73, v73, v161, v130
	v_fma_f32 v74, v74, v162, v130
	v_fma_f32 v75, v75, v163, v130
	v_fma_f32 v64, v64, v164, v130
	v_fma_f32 v65, v65, v165, v130
	v_fma_f32 v66, v66, v166, v130
	v_fma_f32 v67, v67, v167, v130
	v_cvt_pk_bf16_f32 v88, v88, v89
	v_cvt_pk_bf16_f32 v89, v90, v91
	v_cvt_pk_bf16_f32 v80, v80, v81
	v_cvt_pk_bf16_f32 v81, v82, v83
	v_cvt_pk_bf16_f32 v72, v72, v73
	v_cvt_pk_bf16_f32 v73, v74, v75
	v_cvt_pk_bf16_f32 v64, v64, v65
	v_cvt_pk_bf16_f32 v65, v66, v67
	s_waitcnt lgkmcnt(0)
; DEVI unsigned pk_bf16(float lo, float hi) { unsigned r; asm volatile("v_cvt_pk_bf16_f32 %0, %1, %2" : "=v"(r) : "v"(lo), "v"(hi)); return r; }
;   DEVI void operator()(int row0, int colb, int fr, const f32x4& b0, const f32x4& b1, const f32x4& rv, const bool nrm, const Pre& q) const {
;     f32x4 a0, a1;
; #pragma unroll
;     for (int j = 0; j < 4; ++j) { a0[j] = b0[j] * rv[j] + q.s0; a1[j] = b1[j] * rv[j] + q.s1; }
;     if (colb < 1280 || colb >= 1920) {
; #pragma unroll
;       for (int n = 0; n < 2; ++n) {
;         const int pc = colb + n * 16 + fr; const int ptc = pc < 1280 ? pc : pc - 640;
;         const f32x4& a = n ? a1 : a0;
;         uint2 o; o.x = pk_bf16(a[0], a[1]); o.y = pk_bf16(a[2], a[3]);
;         *(uint2*)(pt + (size_t)ptc * T + row0) = o;
;       }
	global_store_dwordx4 v189, v[132:135], s[46:47]
	global_store_dwordx4 v190, v[136:139], s[46:47]
	ds_read_b128 v[140:143], v188 offset:2048
	ds_read_b128 v[144:147], v188 offset:3072
	ds_write_b64 v184, v[88:89]
	ds_write_b64 v185, v[80:81]
	ds_write_b64 v186, v[72:73]
	ds_write_b64 v187, v[64:65]
	v_fma_f32 v92, v92, v152, v131
	v_fma_f32 v93, v93, v153, v131
	v_fma_f32 v94, v94, v154, v131
	v_fma_f32 v95, v95, v155, v131
	v_fma_f32 v84, v84, v156, v131
	v_fma_f32 v85, v85, v157, v131
	v_fma_f32 v86, v86, v158, v131
	v_fma_f32 v87, v87, v159, v131
	v_fma_f32 v76, v76, v160, v131
	v_fma_f32 v77, v77, v161, v131
	v_fma_f32 v78, v78, v162, v131
	v_fma_f32 v79, v79, v163, v131
	v_fma_f32 v68, v68, v164, v131
	v_fma_f32 v69, v69, v165, v131
	v_fma_f32 v70, v70, v166, v131
	v_fma_f32 v71, v71, v167, v131
	v_cvt_pk_bf16_f32 v92, v92, v93
	v_cvt_pk_bf16_f32 v93, v94, v95
	v_cvt_pk_bf16_f32 v84, v84, v85
	v_cvt_pk_bf16_f32 v85, v86, v87
	v_cvt_pk_bf16_f32 v76, v76, v77
	v_cvt_pk_bf16_f32 v77, v78, v79
	v_cvt_pk_bf16_f32 v68, v68, v69
	v_cvt_pk_bf16_f32 v69, v70, v71
	s_waitcnt lgkmcnt(0)
	s_add_u32 s38, s46, 0x110000
	s_addc_u32 s39, s47, 0
	global_store_dwordx4 v189, v[140:143], s[38:39]
	global_store_dwordx4 v190, v[144:147], s[38:39]
	ds_read_b128 v[132:135], v188
	ds_read_b128 v[136:139], v188 offset:1024
	ds_write_b64 v184, v[92:93] offset:2048
	ds_write_b64 v185, v[84:85] offset:2048
	ds_write_b64 v186, v[76:77] offset:2048
	ds_write_b64 v187, v[68:69] offset:2048
	v_fma_f32 v56, v56, v168, v128
	v_fma_f32 v57, v57, v169, v128
	v_fma_f32 v58, v58, v170, v128
	v_fma_f32 v59, v59, v171, v128
	v_fma_f32 v48, v48, v172, v128
	v_fma_f32 v49, v49, v173, v128
	v_fma_f32 v50, v50, v174, v128
	v_fma_f32 v51, v51, v175, v128
	v_fma_f32 v40, v40, v176, v128
	v_fma_f32 v41, v41, v177, v128
	v_fma_f32 v42, v42, v178, v128
	v_fma_f32 v43, v43, v179, v128
	v_fma_f32 v32, v32, v180, v128
	v_fma_f32 v33, v33, v181, v128
	v_fma_f32 v34, v34, v182, v128
	v_fma_f32 v35, v35, v183, v128
	v_cvt_pk_bf16_f32 v56, v56, v57
	v_cvt_pk_bf16_f32 v57, v58, v59
	v_cvt_pk_bf16_f32 v48, v48, v49
	v_cvt_pk_bf16_f32 v49, v50, v51
	v_cvt_pk_bf16_f32 v40, v40, v41
	v_cvt_pk_bf16_f32 v41, v42, v43
	v_cvt_pk_bf16_f32 v32, v32, v33
	v_cvt_pk_bf16_f32 v33, v34, v35
	s_waitcnt lgkmcnt(0)
	s_add_u32 s38, s46, 0x880000
	s_addc_u32 s39, s47, 0
	global_store_dwordx4 v189, v[132:135], s[38:39]
	global_store_dwordx4 v190, v[136:139], s[38:39]
	ds_read_b128 v[140:143], v188 offset:2048
	ds_read_b128 v[144:147], v188 offset:3072
	ds_write_b64 v184, v[56:57]
	ds_write_b64 v185, v[48:49]
	ds_write_b64 v186, v[40:41]
	ds_write_b64 v187, v[32:33]
	v_fma_f32 v60, v60, v168, v129
	v_fma_f32 v61, v61, v169, v129
	v_fma_f32 v62, v62, v170, v129
	v_fma_f32 v63, v63, v171, v129
	v_fma_f32 v52, v52, v172, v129
	v_fma_f32 v53, v53, v173, v129
	v_fma_f32 v54, v54, v174, v129
	v_fma_f32 v55, v55, v175, v129
	v_fma_f32 v44, v44, v176, v129
	v_fma_f32 v45, v45, v177, v129
	v_fma_f32 v46, v46, v178, v129
	v_fma_f32 v47, v47, v179, v129
	v_fma_f32 v36, v36, v180, v129
	v_fma_f32 v37, v37, v181, v129
	v_fma_f32 v38, v38, v182, v129
	v_fma_f32 v39, v39, v183, v129
	v_cvt_pk_bf16_f32 v60, v60, v61
	v_cvt_pk_bf16_f32 v61, v62, v63
	v_cvt_pk_bf16_f32 v52, v52, v53
	v_cvt_pk_bf16_f32 v53, v54, v55
	v_cvt_pk_bf16_f32 v44, v44, v45
	v_cvt_pk_bf16_f32 v45, v46, v47
	v_cvt_pk_bf16_f32 v36, v36, v37
	v_cvt_pk_bf16_f32 v37, v38, v39
	s_waitcnt lgkmcnt(0)
	s_add_u32 s38, s46, 0x990000
	s_addc_u32 s39, s47, 0
	global_store_dwordx4 v189, v[140:143], s[38:39]
	global_store_dwordx4 v190, v[144:147], s[38:39]
	ds_read_b128 v[132:135], v188
	ds_read_b128 v[136:139], v188 offset:1024
	ds_write_b64 v184, v[60:61] offset:2048
	ds_write_b64 v185, v[52:53] offset:2048
	ds_write_b64 v186, v[44:45] offset:2048
	ds_write_b64 v187, v[36:37] offset:2048
	v_fma_f32 v24, v24, v168, v130
	v_fma_f32 v25, v25, v169, v130
	v_fma_f32 v26, v26, v170, v130
	v_fma_f32 v27, v27, v171, v130
	v_fma_f32 v16, v16, v172, v130
	v_fma_f32 v17, v17, v173, v130
	v_fma_f32 v18, v18, v174, v130
	v_fma_f32 v19, v19, v175, v130
	v_fma_f32 v8, v8, v176, v130
	v_fma_f32 v9, v9, v177, v130
	v_fma_f32 v10, v10, v178, v130
	v_fma_f32 v11, v11, v179, v130
	v_fma_f32 v0, v0, v180, v130
	v_fma_f32 v1, v1, v181, v130
	v_fma_f32 v2, v2, v182, v130
	v_fma_f32 v3, v3, v183, v130
	v_cvt_pk_bf16_f32 v24, v24, v25
	v_cvt_pk_bf16_f32 v25, v26, v27
	v_cvt_pk_bf16_f32 v16, v16, v17
	v_cvt_pk_bf16_f32 v17, v18, v19
	v_cvt_pk_bf16_f32 v8, v8, v9
	v_cvt_pk_bf16_f32 v9, v10, v11
	v_cvt_pk_bf16_f32 v0, v0, v1
	v_cvt_pk_bf16_f32 v1, v2, v3
	s_waitcnt lgkmcnt(0)
	s_add_u32 s38, s46, 0x100
	s_addc_u32 s39, s47, 0
	global_store_dwordx4 v189, v[132:135], s[38:39]
	global_store_dwordx4 v190, v[136:139], s[38:39]
	ds_read_b128 v[140:143], v188 offset:2048
	ds_read_b128 v[144:147], v188 offset:3072
	ds_write_b64 v184, v[24:25]
	ds_write_b64 v185, v[16:17]
	ds_write_b64 v186, v[8:9]
	ds_write_b64 v187, v[0:1]
	v_fma_f32 v28, v28, v168, v131
	v_fma_f32 v29, v29, v169, v131
	v_fma_f32 v30, v30, v170, v131
	v_fma_f32 v31, v31, v171, v131
	v_fma_f32 v20, v20, v172, v131
	v_fma_f32 v21, v21, v173, v131
	v_fma_f32 v22, v22, v174, v131
	v_fma_f32 v23, v23, v175, v131
	v_fma_f32 v12, v12, v176, v131
	v_fma_f32 v13, v13, v177, v131
	v_fma_f32 v14, v14, v178, v131
	v_fma_f32 v15, v15, v179, v131
	v_fma_f32 v4, v4, v180, v131
	v_fma_f32 v5, v5, v181, v131
	v_fma_f32 v6, v6, v182, v131
	v_fma_f32 v7, v7, v183, v131
	v_cvt_pk_bf16_f32 v28, v28, v29
	v_cvt_pk_bf16_f32 v29, v30, v31
	v_cvt_pk_bf16_f32 v20, v20, v21
	v_cvt_pk_bf16_f32 v21, v22, v23
	v_cvt_pk_bf16_f32 v12, v12, v13
	v_cvt_pk_bf16_f32 v13, v14, v15
	v_cvt_pk_bf16_f32 v4, v4, v5
	v_cvt_pk_bf16_f32 v5, v6, v7
	s_waitcnt lgkmcnt(0)
	s_add_u32 s38, s46, 0x110100
	s_addc_u32 s39, s47, 0
	global_store_dwordx4 v189, v[140:143], s[38:39]
	global_store_dwordx4 v190, v[144:147], s[38:39]
	ds_read_b128 v[132:135], v188
	ds_read_b128 v[136:139], v188 offset:1024
	ds_write_b64 v184, v[28:29] offset:2048
	ds_write_b64 v185, v[20:21] offset:2048
	ds_write_b64 v186, v[12:13] offset:2048
	ds_write_b64 v187, v[4:5] offset:2048
	s_waitcnt lgkmcnt(0)
	s_add_u32 s38, s46, 0x880100
	s_addc_u32 s39, s47, 0
	global_store_dwordx4 v189, v[132:135], s[38:39]
	global_store_dwordx4 v190, v[136:139], s[38:39]
	ds_read_b128 v[140:143], v188 offset:2048
	ds_read_b128 v[144:147], v188 offset:3072
	s_waitcnt lgkmcnt(0)
	s_add_u32 s38, s46, 0x990100
	s_addc_u32 s39, s47, 0
	global_store_dwordx4 v189, v[140:143], s[38:39]
	global_store_dwordx4 v190, v[144:147], s[38:39]
	s_branch .LBB0_1095

; DEVI unsigned pk_bf16(float lo, float hi) { unsigned r; asm volatile("v_cvt_pk_bf16_f32 %0, %1, %2" : "=v"(r) : "v"(lo), "v"(hi)); return r; }
;   DEVI void operator()(int row0, int colb, int fr, const f32x4& b0, const f32x4& b1, const f32x4& rv, const bool nrm, const Pre& q) const {
;     ...
;     if (colb < 1280 || colb >= 1920) {
; #pragma unroll
;       for (int n = 0; n < 2; ++n) {
;         const int pc = colb + n * 16 + fr; const int ptc = pc < 1280 ? pc : pc - 640;
;         const f32x4& a = n ? a1 : a0;
;         uint2 o; o.x = pk_bf16(a[0], a[1]); o.y = pk_bf16(a[2], a[3]);
;         *(uint2*)(pt + (size_t)ptc * T + row0) = o;
;       }
.LBB0_1119:
	s_cmpk_lt_u32 s40, 0x401
	s_cbranch_scc0 .Lmy_p4_compiled
	s_branch .Lmy_p4_pt
